# P1 column-tile rotation 10 -> 4
# speedup vs baseline: 1.0145x; 1.0032x over previous
.LBB0_103:
	s_cmp_lt_i32 s82, 2
	s_cselect_b64 s[4:5], -1, 0
	s_add_u32 s6, s80, 0x1100000
	v_writelane_b32 v255, s84, 25
	s_addc_u32 s7, s81, 0
	v_writelane_b32 v255, s6, 26
	s_nop 1
	v_writelane_b32 v255, s7, 27
	s_add_u32 s6, s80, 0x1300000
	s_addc_u32 s7, s81, 0
	v_writelane_b32 v255, s6, 28
	s_nop 1
	v_writelane_b32 v255, s7, 29
	s_add_u32 s6, s80, 0x1b00000
	s_addc_u32 s7, s81, 0
	s_add_u32 s69, s80, 0x2600000
	v_writelane_b32 v255, s6, 30
	s_addc_u32 s70, s81, 0
	s_nop 0
	v_writelane_b32 v255, s7, 31
	s_add_u32 s6, s80, 0x2c00000
	s_addc_u32 s7, s81, 0
	s_add_u32 s60, s80, 0x8c00000
	s_addc_u32 s61, s81, 0
	s_add_u32 s96, s80, 0xdc00000
	s_addc_u32 s91, s81, 0
	s_add_u32 s62, s80, 0x7c00000
	v_writelane_b32 v255, s6, 32
	s_addc_u32 s63, s81, 0
	s_and_b64 s[28:29], s[4:5], s[0:1]
	v_writelane_b32 v255, s7, 33
	s_andn2_b64 vcc, exec, s[28:29]
	s_cbranch_vccnz .LBB0_220
	s_cmpk_lt_i32 s2, 0x590
	s_cselect_b64 s[4:5], -1, 0
	s_cmpk_gt_i32 s2, 0x58f
	v_readfirstlane_b32 s6, v216
	s_cbranch_scc1 .LBB0_107
	s_cmpk_gt_i32 s2, 0x57f
	s_cbranch_scc1 .LBB0_108
	s_ashr_i32 s0, s2, 31
	s_lshr_b32 s0, s0, 29
	s_add_i32 s0, s2, s0
	s_ashr_i32 s1, s0, 3
	s_and_b32 s0, s0, -8
	s_sub_i32 s0, s2, s0
	s_cmp_lt_i32 s0, 0
	s_movk_i32 s7, 0xb1
	s_cselect_b32 s7, s7, 0xb0
	s_mul_i32 s0, s0, s7
	s_add_i32 s0, s0, s1
	s_mul_hi_i32 s1, s0, 0x2e8ba2e9
	s_lshr_b32 s7, s1, 31
	s_ashr_i32 s1, s1, 5
	s_add_i32 s1, s1, s7
	s_lshl_b32 s7, s1, 3
	s_mulk_i32 s1, 0xb0
	s_sub_i32 s0, s0, s1
	s_sext_i32_i16 s1, s0
	s_bfe_u32 s1, s1, 0x3001c
	s_add_i32 s1, s0, s1
	s_bfe_u32 s8, s1, 0xd0003
	s_and_b32 s1, s1, 0xfff8
	s_sub_i32 s0, s0, s1
	s_sext_i32_i16 s0, s0
	s_add_i32 s8, s8, 4
	s_add_i32 s38, s7, s0
	s_bfe_i32 s0, s8, 0x80000
	s_mul_i32 s0, s0, 0xffbb
	s_bfe_u32 s0, s0, 0x80008
	s_add_i32 s0, s0, s8
	s_bfe_i32 s1, s0, 0x80000
	s_and_b32 s1, 0xffff, s1
	s_lshr_b32 s1, s1, 4
	s_bfe_u32 s0, s0, 0x10007
	s_add_i32 s0, s1, s0
	s_mul_i32 s0, s0, 22
	s_sub_i32 s0, s8, s0
	s_mov_b32 s59, 0
	s_sext_i32_i8 s90, s0
	s_mov_b64 s[0:1], -1
	s_andn2_b64 vcc, exec, s[4:5]
	v_lshlrev_b32_e32 v16, 2, v216
	s_cbranch_vccz .LBB0_109
	s_branch .LBB0_178

.LBB0_117:
	s_andn2_b64 vcc, exec, s[12:13]
	s_mov_b32 s69, 1
	s_cbranch_vccnz .LBB0_119
	s_ashr_i32 s5, s4, 31
	s_lshr_b32 s5, s5, 29
	s_add_i32 s5, s4, s5
	s_ashr_i32 s12, s5, 3
	s_and_b32 s5, s5, -8
	s_sub_i32 s4, s4, s5
	s_cmp_lt_i32 s4, 0
	s_movk_i32 s5, 0xb1
	s_cselect_b32 s5, s5, 0xb0
	s_mul_i32 s4, s4, s5
	s_add_i32 s4, s4, s12
	s_mul_hi_i32 s5, s4, 0x2e8ba2e9
	s_lshr_b32 s12, s5, 31
	s_ashr_i32 s5, s5, 5
	s_add_i32 s5, s5, s12
	s_lshl_b32 s12, s5, 3
	s_sub_i32 s13, 64, s12
	s_min_i32 s13, s13, 8
	s_abs_i32 s14, s13
	v_cvt_f32_u32_e32 v0, s14
	s_sub_i32 s16, 0, s14
	s_mulk_i32 s5, 0xb0
	s_sub_i32 s4, s4, s5
	v_rcp_iflag_f32_e32 v0, v0
	s_abs_i32 s5, s4
	s_xor_b32 s15, s4, s13
	s_ashr_i32 s15, s15, 31
	v_mul_f32_e32 v0, 0x4f7ffffe, v0
	v_cvt_u32_f32_e32 v0, v0
	s_mov_b32 s69, 0
	v_readfirstlane_b32 s17, v0
	s_mul_i32 s16, s16, s17
	s_mul_hi_u32 s16, s17, s16
	s_add_i32 s17, s17, s16
	s_mul_hi_u32 s16, s5, s17
	s_mul_i32 s17, s16, s14
	s_sub_i32 s5, s5, s17
	s_add_i32 s17, s16, 1
	s_sub_i32 s18, s5, s14
	s_cmp_ge_u32 s5, s14
	s_cselect_b32 s16, s17, s16
	s_cselect_b32 s5, s18, s5
	s_add_i32 s17, s16, 1
	s_cmp_ge_u32 s5, s14
	s_cselect_b32 s5, s17, s16
	s_xor_b32 s5, s5, s15
	s_sub_i32 s5, s5, s15
	s_mul_i32 s13, s5, s13
	s_sub_i32 s4, s4, s13
	s_add_i32 s5, s5, 4
	s_add_i32 s42, s12, s4
	s_sext_i32_i16 s4, s5
	s_mulk_i32 s4, 0xba3
	s_lshr_b32 s12, s4, 31
	s_lshr_b32 s4, s4, 16
	s_add_i32 s4, s4, s12
	s_mul_i32 s4, s4, 22
	s_sub_i32 s4, s5, s4
	s_sext_i32_i16 s44, s4
